# scan: prefetch loads interleaved into the MFMA stream
# speedup vs baseline: 1.0070x; 1.0008x over previous
.LBB0_487:
	s_and_b64 vcc, exec, s[0:1]
	s_cbranch_vccz .LBB0_397
	v_mov_b32_e32 v76, v198
	v_mov_b64_e32 v[4:5], s[16:17]
	flat_load_dwordx2 v[100:101], v[4:5]
	s_lshl_b32 s4, s75, 6
	s_and_b32 s0, s75, 1
	s_ashr_i32 s1, s75, 3
	s_and_b32 s4, s4, 0xffffff80
	v_add_u32_e32 v78, 0x100, v76
	v_add_u32_e32 v84, 0x200, v76
	v_add_u32_e32 v86, 0x300, v76
	v_add_u32_e32 v88, 0x400, v76
	v_add_u32_e32 v90, 0x500, v76
	v_add_u32_e32 v92, 0x600, v76
	v_add_u32_e32 v94, 0x700, v76
	s_mul_hi_i32 s7, s1, 0x3800000
	s_mul_i32 s8, s1, 0x3800000
	s_lshl_b32 s9, s0, 6
	s_lshl_b32 s18, s0, 13
	v_ashrrev_i32_e32 v77, 31, v76
	v_ashrrev_i32_e32 v79, 31, v78
	v_ashrrev_i32_e32 v85, 31, v84
	v_ashrrev_i32_e32 v87, 31, v86
	v_ashrrev_i32_e32 v89, 31, v88
	v_ashrrev_i32_e32 v91, 31, v90
	v_ashrrev_i32_e32 v93, 31, v92
	v_ashrrev_i32_e32 v95, 31, v94
	v_lshlrev_b64 v[96:97], 4, v[76:77]
	v_lshlrev_b64 v[98:99], 4, v[78:79]
	v_lshlrev_b64 v[110:111], 4, v[84:85]
	v_lshlrev_b64 v[108:109], 4, v[86:87]
	v_lshlrev_b64 v[106:107], 4, v[88:89]
	v_lshlrev_b64 v[104:105], 4, v[90:91]
	v_lshlrev_b64 v[122:123], 4, v[92:93]
	v_lshlrev_b64 v[120:121], 4, v[94:95]
	s_lshl_b32 s5, s75, 7
	s_and_b32 s10, s5, 0x300
	s_ashr_i32 s5, s4, 31
	v_and_b32_e32 v79, 63, v76
	v_bfe_u32 v87, v76, 4, 2
	v_ashrrev_i32_e32 v77, 6, v76
	s_mul_i32 s52, s4, 0x12000
	v_lshlrev_b32_e32 v78, 4, v78
	v_lshlrev_b32_e32 v89, 4, v90
	v_lshlrev_b32_e32 v90, 4, v92
	v_lshl_add_u32 v2, v79, 4, 0
	v_lshlrev_b32_e32 v92, 3, v79
	v_mul_hi_u32_u24_e32 v79, 0x7000, v87
	v_mul_u32_u24_e32 v87, 0x7000, v87
	v_and_b32_e32 v85, 15, v76
	s_mul_hi_i32 s11, s4, 0x12000
	v_lshlrev_b32_e32 v1, 4, v76
	v_lshl_add_u32 v76, v77, 4, s9
	v_add_u32_e32 v124, 0, v78
	v_or_b32_e32 v79, s7, v79
	v_or_b32_e32 v78, s8, v87
	v_mad_i64_i32 v[102:103], s[8:9], s4, v210, v[96:97]
	v_lshl_add_u32 v93, v77, 11, 0
	v_ashrrev_i32_e32 v77, 31, v76
	v_or_b32_e32 v78, s10, v78
	v_mov_b32_e32 v4, 0
	v_lshlrev_b32_e32 v84, 4, v84
	v_lshlrev_b32_e32 v86, 4, v86
	v_lshlrev_b32_e32 v88, 4, v88
	v_lshlrev_b32_e32 v91, 4, v94
	v_lshl_add_u64 v[114:115], v[76:77], 1, v[78:79]
	s_movk_i32 s6, 0x7f
	v_mov_b32_e32 v5, v4
	v_mov_b32_e32 v6, v4
	v_mov_b32_e32 v7, v4
	v_mov_b32_e32 v16, v4
	v_mov_b32_e32 v17, v4
	v_mov_b32_e32 v18, v4
	v_mov_b32_e32 v19, v4
	v_add_u32_e32 v1, 0, v1
	v_add_u32_e32 v125, 0, v84
	v_add_u32_e32 v126, 0, v86
	v_add_u32_e32 v127, 0, v88
	v_add_u32_e32 v128, 0, v89
	v_add_u32_e32 v129, 0, v90
	v_add_u32_e32 v130, 0, v91
	v_add_u32_e32 v131, v93, v92
	s_waitcnt vmcnt(0) lgkmcnt(0)
	v_readfirstlane_b32 s86, v100
	v_readfirstlane_b32 s87, v101
	v_mad_i64_i32 v[8:9], s[0:1], s4, v210, v[100:101]
	v_lshl_add_u64 v[10:11], v[8:9], 0, s[34:35]
	v_lshl_add_u64 v[8:9], v[8:9], 0, s[44:45]
	v_lshl_add_u64 v[12:13], v[10:11], 0, v[96:97]
	v_lshl_add_u64 v[14:15], v[10:11], 0, v[98:99]
	v_lshl_add_u64 v[20:21], v[10:11], 0, v[110:111]
	v_lshl_add_u64 v[24:25], v[10:11], 0, v[108:109]
	v_lshl_add_u64 v[28:29], v[10:11], 0, v[106:107]
	v_lshl_add_u64 v[32:33], v[10:11], 0, v[104:105]
	v_lshl_add_u64 v[36:37], v[10:11], 0, v[122:123]
	v_lshl_add_u64 v[40:41], v[10:11], 0, v[120:121]
	v_lshl_add_u64 v[30:31], v[8:9], 0, v[96:97]
	v_lshl_add_u64 v[34:35], v[8:9], 0, v[98:99]
	v_lshl_add_u64 v[38:39], v[8:9], 0, v[110:111]
	v_lshl_add_u64 v[42:43], v[8:9], 0, v[108:109]
	v_lshl_add_u64 v[44:45], v[8:9], 0, v[106:107]
	v_lshl_add_u64 v[72:73], v[10:11], 0, s[18:19]
	v_lshl_add_u64 v[46:47], v[8:9], 0, v[104:105]
	global_load_dwordx4 v[8:11], v[12:13], off
	s_nop 0
	global_load_dwordx4 v[12:15], v[14:15], off
	s_nop 0
	global_load_dwordx4 v[20:23], v[20:21], off
	s_nop 0
	global_load_dwordx4 v[24:27], v[24:25], off
	s_nop 0
	global_load_dwordx4 v[48:51], v[30:31], off
	global_load_dwordx4 v[52:55], v[34:35], off
	s_nop 0
	global_load_dwordx4 v[28:31], v[28:29], off
	s_nop 0
	global_load_dwordx4 v[32:35], v[32:33], off
	s_nop 0
	global_load_dwordx4 v[56:59], v[38:39], off
	global_load_dwordx4 v[60:63], v[42:43], off
	s_nop 0
	global_load_dwordx4 v[36:39], v[36:37], off
	s_nop 0
	global_load_dwordx4 v[40:43], v[40:41], off
	s_nop 0
	global_load_dwordx4 v[64:67], v[44:45], off
	global_load_dwordx4 v[68:71], v[46:47], off
	v_lshl_add_u64 v[44:45], v[72:73], 0, s[46:47]
	v_lshl_add_u64 v[46:47], v[44:45], 0, v[96:97]
	v_lshl_add_u64 v[44:45], v[44:45], 0, v[98:99]
	global_load_dwordx4 v[72:75], v[46:47], off
	global_load_dwordx4 v[80:83], v[44:45], off
	s_lshl_b64 s[0:1], s[4:5], 2
	s_add_u32 s0, s0, 0x2ce00000
	s_addc_u32 s1, s1, 0
	s_or_b32 s7, s52, s18
	v_mad_i64_i32 v[104:105], s[8:9], s4, v210, v[104:105]
	v_mad_i64_i32 v[106:107], s[8:9], s4, v210, v[106:107]
	v_mad_i64_i32 v[108:109], s[8:9], s4, v210, v[108:109]
	v_mad_i64_i32 v[110:111], s[8:9], s4, v210, v[110:111]
	v_mad_i64_i32 v[112:113], s[4:5], s4, v210, v[98:99]
	s_add_u32 s4, s7, 0x2e020000
	s_addc_u32 s5, s11, 0
	v_lshl_add_u64 v[116:117], s[4:5], 0, v[98:99]
	v_lshl_add_u64 v[118:119], s[4:5], 0, v[96:97]
	s_add_u32 s4, s52, 0x2e012000
	s_addc_u32 s5, s11, 0
	v_mov_b32_e32 v44, v4
	v_mov_b32_e32 v45, v4
	v_mov_b32_e32 v46, v4
	v_mov_b32_e32 v47, v4
	v_lshl_or_b32 v114, v85, 1, v114
	v_lshl_add_u64 v[120:121], s[4:5], 0, v[120:121]
	v_lshl_add_u64 v[122:123], s[4:5], 0, v[122:123]
	v_mov_b32_e32 v76, v4
	v_mov_b32_e32 v77, v4
	v_mov_b32_e32 v78, v4
	v_mov_b32_e32 v79, v4
	v_mov_b32_e32 v84, v4
	v_mov_b32_e32 v85, v4
	v_mov_b32_e32 v86, v4
	v_mov_b32_e32 v87, v4
	v_mov_b32_e32 v88, v4
	v_mov_b32_e32 v89, v4
	v_mov_b32_e32 v90, v4
	v_mov_b32_e32 v91, v4
	v_mov_b32_e32 v92, v4
	v_mov_b32_e32 v93, v4
	v_mov_b32_e32 v94, v4
	v_mov_b32_e32 v95, v4
	v_mov_b32_e32 v96, v4
	v_mov_b32_e32 v97, v4
	v_mov_b32_e32 v98, v4
	v_mov_b32_e32 v99, v4
	v_lshl_add_u64 v[196:197], v[100:101], 0, s[0:1]
	global_load_dword v196, v[196:197], off
	s_waitcnt vmcnt(15)
	ds_write_b128 v1, v[8:11]
	s_waitcnt vmcnt(11)
	ds_write_b128 v1, v[48:51] offset:32768
	ds_write_b128 v124, v[12:15]
	s_waitcnt vmcnt(10)
	ds_write_b128 v124, v[52:55] offset:32768
	ds_write_b128 v125, v[20:23]
	s_waitcnt vmcnt(7)
	ds_write_b128 v125, v[56:59] offset:32768
	ds_write_b128 v126, v[24:27]
	s_waitcnt vmcnt(6)
	ds_write_b128 v126, v[60:63] offset:32768
	ds_write_b128 v127, v[28:31]
	s_waitcnt vmcnt(3)
	ds_write_b128 v127, v[64:67] offset:32768
	ds_write_b128 v128, v[32:35]
	s_waitcnt vmcnt(2)
	ds_write_b128 v128, v[68:71] offset:32768
	ds_write_b128 v129, v[36:39]
	ds_write_b128 v130, v[40:43]
	s_waitcnt vmcnt(1)
	ds_write_b128 v129, v[72:75] offset:32768
	s_waitcnt vmcnt(0)
	ds_write_b128 v130, v[80:83] offset:32768
	s_waitcnt lgkmcnt(0)
	s_barrier
	s_branch .LBB0_490

.LBB0_490:
	s_cmp_lg_u32 s6, 0
	s_cselect_b64 s[4:5], -1, 0
	s_cmp_eq_u32 s6, 0
	s_cbranch_scc1 .LBB0_492
	v_lshl_add_u64 v[48:49], v[100:101], 0, v[102:103]
	v_add_co_u32_e32 v8, vcc, 0x2e012000, v48
	v_lshl_add_u64 v[50:51], v[100:101], 0, v[112:113]
	s_nop 0
	v_addc_co_u32_e32 v9, vcc, 0, v49, vcc
	v_add_co_u32_e32 v12, vcc, 0x2e012000, v50
	v_lshl_add_u64 v[56:57], v[100:101], 0, v[110:111]
	s_nop 0
	v_addc_co_u32_e32 v13, vcc, 0, v51, vcc
	v_add_co_u32_e32 v20, vcc, 0x2e012000, v56
	v_lshl_add_u64 v[58:59], v[100:101], 0, v[108:109]
	s_nop 0
	v_addc_co_u32_e32 v21, vcc, 0, v57, vcc
	v_add_co_u32_e32 v24, vcc, 0x2e012000, v58
	v_lshl_add_u64 v[64:65], v[100:101], 0, v[106:107]
	s_nop 0
	v_addc_co_u32_e32 v25, vcc, 0, v59, vcc
	v_add_co_u32_e32 v28, vcc, 0x2e012000, v64
	v_lshl_add_u64 v[66:67], v[100:101], 0, v[104:105]
	s_nop 0
	v_addc_co_u32_e32 v29, vcc, 0, v65, vcc
	v_add_co_u32_e32 v32, vcc, 0x2e012000, v66
	v_lshl_add_u64 v[36:37], v[100:101], 0, v[122:123]
	s_nop 0
	v_addc_co_u32_e32 v33, vcc, 0, v67, vcc
	v_add_co_u32_e32 v48, vcc, s42, v48
	v_lshl_add_u64 v[40:41], v[100:101], 0, v[120:121]
	s_nop 0
	v_addc_co_u32_e32 v49, vcc, 0, v49, vcc
	v_add_co_u32_e32 v52, vcc, s42, v50
	v_lshl_add_u64 v[72:73], v[100:101], 0, v[118:119]
	s_nop 0
	v_addc_co_u32_e32 v53, vcc, 0, v51, vcc
	v_add_co_u32_e32 v56, vcc, s42, v56
	v_lshl_add_u64 v[80:81], v[100:101], 0, v[116:117]
	s_nop 0
	v_addc_co_u32_e32 v57, vcc, 0, v57, vcc
	v_add_co_u32_e32 v60, vcc, s42, v58
	s_nop 0
	v_addc_co_u32_e32 v61, vcc, 0, v59, vcc
	v_add_co_u32_e32 v64, vcc, s42, v64
	s_nop 0
	v_addc_co_u32_e32 v65, vcc, 0, v65, vcc
	v_add_co_u32_e32 v68, vcc, s42, v66
	s_nop 0
	v_addc_co_u32_e32 v69, vcc, 0, v67, vcc
	s_nop 0
	s_nop 0
	s_nop 0
	s_nop 0
	s_nop 0
	s_nop 0
	s_nop 0
	s_nop 0
	s_nop 0
.LBB0_492:
	ds_read_b128 v[212:215], v2
	ds_read_b128 v[216:219], v2 offset:4096
	ds_read_b128 v[220:223], v2 offset:8192
	ds_read_b128 v[224:227], v2 offset:12288
	ds_read_b128 v[228:231], v2 offset:1024
	ds_read2st64_b64 v[188:191], v131 offset0:112 offset1:113
	ds_read2st64_b64 v[192:195], v131 offset0:114 offset1:115
	v_cvt_pk_bf16_f32 v132, v16, v17
	v_cvt_pk_bf16_f32 v133, v18, v19
	v_cvt_pk_bf16_f32 v134, v4, v5
	v_cvt_pk_bf16_f32 v135, v6, v7
	v_cvt_pk_bf16_f32 v136, v44, v45
	v_cvt_pk_bf16_f32 v137, v46, v47
	v_cvt_pk_bf16_f32 v138, v76, v77
	v_cvt_pk_bf16_f32 v139, v78, v79
	v_cvt_pk_bf16_f32 v140, v84, v85
	v_cvt_pk_bf16_f32 v141, v86, v87
	v_cvt_pk_bf16_f32 v142, v88, v89
	v_cvt_pk_bf16_f32 v143, v90, v91
	v_cvt_pk_bf16_f32 v144, v92, v93
	v_cvt_pk_bf16_f32 v145, v94, v95
	v_cvt_pk_bf16_f32 v146, v96, v97
	v_cvt_pk_bf16_f32 v147, v98, v99
	v_add_u32_e32 v197, 0x4000c00, v114
	s_waitcnt lgkmcnt(6)
	v_mfma_f32_16x16x32_bf16 v[156:159], v[212:215], v[132:135], 0
	ds_read_b128 v[232:235], v2 offset:5120
	s_cmp_eq_u32 s6, 0
	s_cbranch_scc1 .Lscan_pf0
	global_load_dwordx4 v[8:11], v[8:9], off
.Lscan_pf0:
	s_waitcnt lgkmcnt(6)
	v_mfma_f32_16x16x32_bf16 v[160:163], v[216:219], v[132:135], 0
	ds_read_b128 v[236:239], v2 offset:9216
	s_waitcnt lgkmcnt(6)
	v_mfma_f32_16x16x32_bf16 v[164:167], v[220:223], v[132:135], 0
	ds_read_b128 v[212:215], v2 offset:13312
	s_cmp_eq_u32 s6, 0
	s_cbranch_scc1 .Lscan_pf1
	global_load_dwordx4 v[12:15], v[12:13], off
.Lscan_pf1:
	s_waitcnt lgkmcnt(6)
	v_mfma_f32_16x16x32_bf16 v[168:171], v[224:227], v[132:135], 0
	ds_read_b128 v[216:219], v2 offset:2048
	s_waitcnt lgkmcnt(6)
	v_mfma_f32_16x16x32_bf16 v[156:159], v[228:231], v[136:139], v[156:159]
	ds_read_b128 v[220:223], v2 offset:6144
	s_waitcnt lgkmcnt(4)
	v_mfma_f32_16x16x32_bf16 v[160:163], v[232:235], v[136:139], v[160:163]
	ds_read_b128 v[224:227], v2 offset:10240
	s_cmp_eq_u32 s6, 0
	s_cbranch_scc1 .Lscan_pf2
	global_load_dwordx4 v[20:23], v[20:21], off
.Lscan_pf2:
	s_waitcnt lgkmcnt(4)
	v_mfma_f32_16x16x32_bf16 v[164:167], v[236:239], v[136:139], v[164:167]
	ds_read_b128 v[228:231], v2 offset:14336
	s_waitcnt lgkmcnt(4)
	v_mfma_f32_16x16x32_bf16 v[168:171], v[212:215], v[136:139], v[168:171]
	ds_read_b128 v[232:235], v2 offset:3072
	s_cmp_eq_u32 s6, 0
	s_cbranch_scc1 .Lscan_pf3
	global_load_dwordx4 v[24:27], v[24:25], off
.Lscan_pf3:
	s_waitcnt lgkmcnt(4)
	v_mfma_f32_16x16x32_bf16 v[156:159], v[216:219], v[140:143], v[156:159]
	ds_read_b128 v[236:239], v2 offset:7168
	s_waitcnt lgkmcnt(4)
	v_mfma_f32_16x16x32_bf16 v[160:163], v[220:223], v[140:143], v[160:163]
	ds_read_b128 v[212:215], v2 offset:11264
	s_waitcnt lgkmcnt(4)
	v_mfma_f32_16x16x32_bf16 v[164:167], v[224:227], v[140:143], v[164:167]
	ds_read_b128 v[216:219], v2 offset:15360
	s_cmp_eq_u32 s6, 0
	s_cbranch_scc1 .Lscan_pf4
	global_load_dwordx4 v[28:31], v[28:29], off
.Lscan_pf4:
	s_waitcnt lgkmcnt(4)
	v_mfma_f32_16x16x32_bf16 v[168:171], v[228:231], v[140:143], v[168:171]
	ds_read_b128 v[220:223], v2 offset:16384
	s_waitcnt lgkmcnt(4)
	v_mfma_f32_16x16x32_bf16 v[156:159], v[232:235], v[144:147], v[156:159]
	ds_read_b128 v[224:227], v2 offset:20480
	s_cmp_eq_u32 s6, 0
	s_cbranch_scc1 .Lscan_pf5
	global_load_dwordx4 v[32:35], v[32:33], off
.Lscan_pf5:
	s_waitcnt lgkmcnt(4)
	v_mfma_f32_16x16x32_bf16 v[160:163], v[236:239], v[144:147], v[160:163]
	ds_read_b128 v[228:231], v2 offset:24576
	s_waitcnt lgkmcnt(4)
	v_mfma_f32_16x16x32_bf16 v[164:167], v[212:215], v[144:147], v[164:167]
	ds_read_b128 v[232:235], v2 offset:28672
	s_waitcnt lgkmcnt(4)
	v_mfma_f32_16x16x32_bf16 v[168:171], v[216:219], v[144:147], v[168:171]
	ds_read_b128 v[236:239], v2 offset:17408
	s_cmp_eq_u32 s6, 0
	s_cbranch_scc1 .Lscan_pf6
	global_load_dwordx4 v[36:39], v[36:37], off
.Lscan_pf6:
	s_waitcnt lgkmcnt(4)
	v_mfma_f32_16x16x32_bf16 v[172:175], v[220:223], v[132:135], 0
	ds_read_b128 v[212:215], v2 offset:21504
	v_pk_mul_f32 v[16:17], v[16:17], v[196:197] op_sel_hi:[1,0]
	v_pk_mul_f32 v[18:19], v[18:19], v[196:197] op_sel_hi:[1,0]
	s_waitcnt lgkmcnt(4)
	v_mfma_f32_16x16x32_bf16 v[176:179], v[224:227], v[132:135], 0
	ds_read_b128 v[216:219], v2 offset:25600
	s_cmp_eq_u32 s6, 0
	s_cbranch_scc1 .Lscan_pf7
	global_load_dwordx4 v[40:43], v[40:41], off
.Lscan_pf7:
	v_pk_mul_f32 v[4:5], v[4:5], v[196:197] op_sel_hi:[1,0]
	v_pk_mul_f32 v[6:7], v[6:7], v[196:197] op_sel_hi:[1,0]
	s_waitcnt lgkmcnt(4)
	v_mfma_f32_16x16x32_bf16 v[180:183], v[228:231], v[132:135], 0
	ds_read_b128 v[220:223], v2 offset:29696
	v_pk_mul_f32 v[44:45], v[44:45], v[196:197] op_sel_hi:[1,0]
	v_pk_mul_f32 v[46:47], v[46:47], v[196:197] op_sel_hi:[1,0]
	v_lshlrev_b32_e32 v240, 16, v188
	v_and_b32_e32 v241, 0xffff0000, v188
	v_lshlrev_b32_e32 v242, 16, v189
	v_and_b32_e32 v243, 0xffff0000, v189
	s_waitcnt lgkmcnt(4)
	v_mfma_f32_16x16x32_bf16 v[184:187], v[232:235], v[132:135], 0
	ds_read_b128 v[224:227], v2 offset:18432
	v_pk_mul_f32 v[76:77], v[76:77], v[196:197] op_sel_hi:[1,0]
	v_pk_mul_f32 v[78:79], v[78:79], v[196:197] op_sel_hi:[1,0]
	v_sub_f32_e32 v156, v240, v156
	v_sub_f32_e32 v157, v241, v157
	v_sub_f32_e32 v158, v242, v158
	v_sub_f32_e32 v159, v243, v159
	s_waitcnt lgkmcnt(4)
	v_mfma_f32_16x16x32_bf16 v[172:175], v[236:239], v[136:139], v[172:175]
	ds_read_b128 v[228:231], v2 offset:22528
	s_cmp_eq_u32 s6, 0
	s_cbranch_scc1 .Lscan_pf8
	global_load_dwordx4 v[48:51], v[48:49], off
.Lscan_pf8:
	v_pk_mul_f32 v[84:85], v[84:85], v[196:197] op_sel_hi:[1,0]
	v_pk_mul_f32 v[86:87], v[86:87], v[196:197] op_sel_hi:[1,0]
	v_lshlrev_b32_e32 v240, 16, v190
	v_and_b32_e32 v241, 0xffff0000, v190
	v_lshlrev_b32_e32 v242, 16, v191
	v_and_b32_e32 v243, 0xffff0000, v191
	s_waitcnt lgkmcnt(4)
	v_mfma_f32_16x16x32_bf16 v[176:179], v[212:215], v[136:139], v[176:179]
	ds_read_b128 v[232:235], v2 offset:26624
	v_pk_mul_f32 v[88:89], v[88:89], v[196:197] op_sel_hi:[1,0]
	v_pk_mul_f32 v[90:91], v[90:91], v[196:197] op_sel_hi:[1,0]
	v_sub_f32_e32 v160, v240, v160
	v_sub_f32_e32 v161, v241, v161
	v_sub_f32_e32 v162, v242, v162
	v_sub_f32_e32 v163, v243, v163
	s_waitcnt lgkmcnt(4)
	v_mfma_f32_16x16x32_bf16 v[180:183], v[216:219], v[136:139], v[180:183]
	ds_read_b128 v[236:239], v2 offset:30720
	s_cmp_eq_u32 s6, 0
	s_cbranch_scc1 .Lscan_pf9
	global_load_dwordx4 v[52:55], v[52:53], off
.Lscan_pf9:
	v_pk_mul_f32 v[92:93], v[92:93], v[196:197] op_sel_hi:[1,0]
	v_pk_mul_f32 v[94:95], v[94:95], v[196:197] op_sel_hi:[1,0]
	v_lshlrev_b32_e32 v240, 16, v192
	v_and_b32_e32 v241, 0xffff0000, v192
	v_lshlrev_b32_e32 v242, 16, v193
	v_and_b32_e32 v243, 0xffff0000, v193
	v_cvt_pk_bf16_f32 v148, v156, v157
	v_cvt_pk_bf16_f32 v149, v158, v159
	v_cvt_pk_bf16_f32 v150, v160, v161
	v_cvt_pk_bf16_f32 v151, v162, v163
	s_waitcnt lgkmcnt(4)
	v_mfma_f32_16x16x32_bf16 v[184:187], v[220:223], v[136:139], v[184:187]
	ds_read_b128 v[212:215], v2 offset:19456
	v_pk_mul_f32 v[96:97], v[96:97], v[196:197] op_sel_hi:[1,0]
	v_pk_mul_f32 v[98:99], v[98:99], v[196:197] op_sel_hi:[1,0]
	v_sub_f32_e32 v164, v240, v164
	v_sub_f32_e32 v165, v241, v165
	v_sub_f32_e32 v166, v242, v166
	v_sub_f32_e32 v167, v243, v167
	s_waitcnt lgkmcnt(4)
	v_mfma_f32_16x16x32_bf16 v[172:175], v[224:227], v[140:143], v[172:175]
	ds_read_b128 v[216:219], v2 offset:23552
	v_lshlrev_b32_e32 v240, 16, v194
	v_and_b32_e32 v241, 0xffff0000, v194
	v_lshlrev_b32_e32 v242, 16, v195
	v_and_b32_e32 v243, 0xffff0000, v195
	s_waitcnt lgkmcnt(4)
	v_mfma_f32_16x16x32_bf16 v[176:179], v[228:231], v[140:143], v[176:179]
	ds_read_b128 v[220:223], v2 offset:27648
	s_cmp_eq_u32 s6, 0
	s_cbranch_scc1 .Lscan_pf10
	global_load_dwordx4 v[56:59], v[56:57], off
.Lscan_pf10:
	v_sub_f32_e32 v168, v240, v168
	v_sub_f32_e32 v169, v241, v169
	v_sub_f32_e32 v170, v242, v170
	v_sub_f32_e32 v171, v243, v171
	s_waitcnt lgkmcnt(4)
	v_mfma_f32_16x16x32_bf16 v[180:183], v[232:235], v[140:143], v[180:183]
	ds_read_b128 v[224:227], v2 offset:31744
	v_cvt_pk_bf16_f32 v152, v164, v165
	v_cvt_pk_bf16_f32 v153, v166, v167
	v_cvt_pk_bf16_f32 v154, v168, v169
	v_cvt_pk_bf16_f32 v155, v170, v171
	s_waitcnt lgkmcnt(4)
	v_mfma_f32_16x16x32_bf16 v[184:187], v[236:239], v[140:143], v[184:187]
	ds_read_b128 v[228:231], v2 offset:49152
	s_cmp_eq_u32 s6, 0
	s_cbranch_scc1 .Lscan_pf11
	global_load_dwordx4 v[60:63], v[60:61], off
.Lscan_pf11:
	s_waitcnt lgkmcnt(4)
	v_mfma_f32_16x16x32_bf16 v[172:175], v[212:215], v[144:147], v[172:175]
	ds_read_b128 v[232:235], v2 offset:51200
	s_cmp_eq_u32 s6, 0
	s_cbranch_scc1 .Lscan_noegl
	v_lshl_add_u64 v[240:241], v[100:101], 0, s[0:1]
	global_load_dword v196, v[240:241], off offset:4
.Lscan_noegl:
	s_waitcnt lgkmcnt(4)
	v_mfma_f32_16x16x32_bf16 v[176:179], v[216:219], v[144:147], v[176:179]
	ds_read_b128 v[236:239], v2 offset:53248
	s_waitcnt lgkmcnt(4)
	v_mfma_f32_16x16x32_bf16 v[180:183], v[220:223], v[144:147], v[180:183]
	ds_read_b128 v[212:215], v2 offset:55296
	s_cmp_eq_u32 s6, 0
	s_cbranch_scc1 .Lscan_pf12
	global_load_dwordx4 v[64:67], v[64:65], off
.Lscan_pf12:
	s_waitcnt lgkmcnt(4)
	v_mfma_f32_16x16x32_bf16 v[184:187], v[224:227], v[144:147], v[184:187]
	ds_read_b128 v[216:219], v2 offset:50176
	s_waitcnt lgkmcnt(4)
	v_mfma_f32_16x16x32_bf16 v[172:175], v[228:231], v[148:151], v[172:175]
	ds_read_b128 v[220:223], v2 offset:52224
	s_cmp_eq_u32 s6, 0
	s_cbranch_scc1 .Lscan_pf13
	global_load_dwordx4 v[68:71], v[68:69], off
.Lscan_pf13:
	s_waitcnt lgkmcnt(4)
	v_mfma_f32_16x16x32_bf16 v[176:179], v[232:235], v[148:151], v[176:179]
	ds_read_b128 v[224:227], v2 offset:54272
	s_waitcnt lgkmcnt(4)
	v_mfma_f32_16x16x32_bf16 v[180:183], v[236:239], v[148:151], v[180:183]
	ds_read_b128 v[228:231], v2 offset:56320
	s_waitcnt lgkmcnt(4)
	v_mfma_f32_16x16x32_bf16 v[184:187], v[212:215], v[148:151], v[184:187]
	ds_read_b128 v[232:235], v2 offset:32768
	s_cmp_eq_u32 s6, 0
	s_cbranch_scc1 .Lscan_pf14
	global_load_dwordx4 v[72:75], v[72:73], off
.Lscan_pf14:
	s_waitcnt lgkmcnt(4)
	v_mfma_f32_16x16x32_bf16 v[172:175], v[216:219], v[152:155], v[172:175]
	ds_read_b128 v[236:239], v2 offset:34816
	s_waitcnt lgkmcnt(4)
	v_mfma_f32_16x16x32_bf16 v[176:179], v[220:223], v[152:155], v[176:179]
	ds_read_b128 v[212:215], v2 offset:36864
	s_cmp_eq_u32 s6, 0
	s_cbranch_scc1 .Lscan_pf15
	global_load_dwordx4 v[80:83], v[80:81], off
.Lscan_pf15:
	s_waitcnt lgkmcnt(4)
	v_mfma_f32_16x16x32_bf16 v[180:183], v[224:227], v[152:155], v[180:183]
	ds_read_b128 v[216:219], v2 offset:38912
	s_waitcnt lgkmcnt(4)
	v_mfma_f32_16x16x32_bf16 v[184:187], v[228:231], v[152:155], v[184:187]
	ds_read_b128 v[220:223], v2 offset:40960
	s_waitcnt lgkmcnt(4)
	v_mfma_f32_16x16x32_bf16 v[16:19], v[232:235], v[148:151], v[16:19]
	ds_read_b128 v[224:227], v2 offset:43008
	s_waitcnt lgkmcnt(4)
	v_mfma_f32_16x16x32_bf16 v[4:7], v[236:239], v[148:151], v[4:7]
	ds_read_b128 v[228:231], v2 offset:45056
	v_bfe_u32 v156, v172, 16, 1
	v_add3_u32 v156, v172, v156, s43
	global_store_short_d16_hi v197, v156, s[86:87]
	v_bfe_u32 v157, v173, 16, 1
	v_add3_u32 v157, v173, v157, s43
	v_add_u32_e32 v189, 0x1c00, v197
	global_store_short_d16_hi v189, v157, s[86:87]
	s_waitcnt lgkmcnt(4)
	v_mfma_f32_16x16x32_bf16 v[44:47], v[212:215], v[148:151], v[44:47]
	ds_read_b128 v[232:235], v2 offset:47104
	v_bfe_u32 v158, v174, 16, 1
	v_add3_u32 v158, v174, v158, s43
	v_add_u32_e32 v190, 0x3800, v197
	global_store_short_d16_hi v190, v158, s[86:87]
	v_bfe_u32 v159, v175, 16, 1
	v_add3_u32 v159, v175, v159, s43
	v_add_u32_e32 v191, 0x5400, v197
	global_store_short_d16_hi v191, v159, s[86:87]
	s_waitcnt lgkmcnt(4)
	v_mfma_f32_16x16x32_bf16 v[76:79], v[216:219], v[148:151], v[76:79]
	ds_read_b128 v[236:239], v2 offset:33792
	s_waitcnt lgkmcnt(4)
	v_mfma_f32_16x16x32_bf16 v[84:87], v[220:223], v[148:151], v[84:87]
	ds_read_b128 v[212:215], v2 offset:35840
	v_bfe_u32 v160, v176, 16, 1
	v_add3_u32 v160, v176, v160, s43
	v_add_u32_e32 v192, 0x1c000, v197
	global_store_short_d16_hi v192, v160, s[86:87]
	v_bfe_u32 v161, v177, 16, 1
	v_add3_u32 v161, v177, v161, s43
	v_add_u32_e32 v193, 0x1dc00, v197
	global_store_short_d16_hi v193, v161, s[86:87]
	s_waitcnt lgkmcnt(4)
	v_mfma_f32_16x16x32_bf16 v[88:91], v[224:227], v[148:151], v[88:91]
	ds_read_b128 v[216:219], v2 offset:37888
	v_bfe_u32 v162, v178, 16, 1
	v_add3_u32 v162, v178, v162, s43
	v_add_u32_e32 v194, 0x1f800, v197
	global_store_short_d16_hi v194, v162, s[86:87]
	v_bfe_u32 v163, v179, 16, 1
	v_add3_u32 v163, v179, v163, s43
	v_add_u32_e32 v195, 0x21400, v197
	global_store_short_d16_hi v195, v163, s[86:87]
	s_waitcnt lgkmcnt(4)
	v_mfma_f32_16x16x32_bf16 v[92:95], v[228:231], v[148:151], v[92:95]
	ds_read_b128 v[220:223], v2 offset:39936
	s_waitcnt lgkmcnt(4)
	v_mfma_f32_16x16x32_bf16 v[96:99], v[232:235], v[148:151], v[96:99]
	ds_read_b128 v[224:227], v2 offset:41984
	v_bfe_u32 v156, v180, 16, 1
	v_add3_u32 v156, v180, v156, s43
	v_add_u32_e32 v188, 0x38000, v197
	global_store_short_d16_hi v188, v156, s[86:87]
	v_bfe_u32 v157, v181, 16, 1
	v_add3_u32 v157, v181, v157, s43
	v_add_u32_e32 v189, 0x39c00, v197
	global_store_short_d16_hi v189, v157, s[86:87]
	s_waitcnt lgkmcnt(4)
	v_mfma_f32_16x16x32_bf16 v[16:19], v[236:239], v[152:155], v[16:19]
	ds_read_b128 v[228:231], v2 offset:44032
	v_bfe_u32 v158, v182, 16, 1
	v_add3_u32 v158, v182, v158, s43
	v_add_u32_e32 v190, 0x3b800, v197
	global_store_short_d16_hi v190, v158, s[86:87]
	v_bfe_u32 v159, v183, 16, 1
	v_add3_u32 v159, v183, v159, s43
	v_add_u32_e32 v191, 0x3d400, v197
	global_store_short_d16_hi v191, v159, s[86:87]
	s_waitcnt lgkmcnt(4)
	v_mfma_f32_16x16x32_bf16 v[4:7], v[212:215], v[152:155], v[4:7]
	ds_read_b128 v[232:235], v2 offset:46080
	s_waitcnt lgkmcnt(4)
	v_mfma_f32_16x16x32_bf16 v[44:47], v[216:219], v[152:155], v[44:47]
	ds_read_b128 v[236:239], v2 offset:48128
	v_bfe_u32 v160, v184, 16, 1
	v_add3_u32 v160, v184, v160, s43
	v_add_u32_e32 v192, 0x54000, v197
	global_store_short_d16_hi v192, v160, s[86:87]
	v_bfe_u32 v161, v185, 16, 1
	v_add3_u32 v161, v185, v161, s43
	v_add_u32_e32 v193, 0x55c00, v197
	global_store_short_d16_hi v193, v161, s[86:87]
	s_waitcnt lgkmcnt(4)
	v_mfma_f32_16x16x32_bf16 v[76:79], v[220:223], v[152:155], v[76:79]
	v_bfe_u32 v162, v186, 16, 1
	v_add3_u32 v162, v186, v162, s43
	v_add_u32_e32 v194, 0x57800, v197
	global_store_short_d16_hi v194, v162, s[86:87]
	v_bfe_u32 v163, v187, 16, 1
	v_add3_u32 v163, v187, v163, s43
	v_add_u32_e32 v195, 0x59400, v197
	global_store_short_d16_hi v195, v163, s[86:87]
	s_waitcnt lgkmcnt(3)
	v_mfma_f32_16x16x32_bf16 v[84:87], v[224:227], v[152:155], v[84:87]
	s_waitcnt lgkmcnt(2)
	v_mfma_f32_16x16x32_bf16 v[88:91], v[228:231], v[152:155], v[88:91]
	s_waitcnt lgkmcnt(1)
	v_mfma_f32_16x16x32_bf16 v[92:95], v[232:235], v[152:155], v[92:95]
	s_waitcnt lgkmcnt(0)
	v_mfma_f32_16x16x32_bf16 v[96:99], v[236:239], v[152:155], v[96:99]
	s_andn2_b64 vcc, exec, s[4:5]
	s_waitcnt lgkmcnt(0)
	s_barrier
	s_cbranch_vccnz .LBB0_489
	s_waitcnt vmcnt(16)
	ds_write_b128 v1, v[8:11]
	ds_write_b128 v1, v[48:51] offset:32768
	ds_write_b128 v124, v[12:15]
	ds_write_b128 v124, v[52:55] offset:32768
	ds_write_b128 v125, v[20:23]
	ds_write_b128 v125, v[56:59] offset:32768
	ds_write_b128 v126, v[24:27]
	ds_write_b128 v126, v[60:63] offset:32768
	ds_write_b128 v127, v[28:31]
	ds_write_b128 v127, v[64:67] offset:32768
	ds_write_b128 v128, v[32:35]
	ds_write_b128 v128, v[68:71] offset:32768
	ds_write_b128 v129, v[36:39]
	ds_write_b128 v129, v[72:75] offset:32768
	ds_write_b128 v130, v[40:43]
	ds_write_b128 v130, v[80:83] offset:32768
	s_branch .LBB0_489
